# onorm prompt loop: the early vmcnt(0) on the first row load (and its 8 consumers) moved below the last load of the pair, waited with vmcnt(7): one serialized memory round trip less per iteration
# speedup vs baseline: 1.0077x; 1.0004x over previous
; DI float siluf_(float x) { return x * sigmoidf_(x); }
; DI void phase_onorm(const Params& p, const Sub& s) {
;     ...
;   for (int r = (s.samp ? MP : 0) + s.vb * 4 + wave; r < rhi; r += 2 * stride) {
;     const bool two = r + stride < rhi;
;     const int rr[2] = {r, two ? r + stride : r};
;     float v[2][16], zz[2][16];
; #pragma unroll
;     for (int q = 0; q < 2; ++q) {
;       const size_t o = (size_t)rr[q] * D + lane * 16;
; #pragma unroll
;       for (int i = 0; i < 4; ++i) { ld_bf4(O + o + i * 4, v[q][4 * i], v[q][4 * i + 1], v[q][4 * i + 2], v[q][4 * i + 3]); ld_bf4(z1 + o + i * 4, zz[q][4 * i], zz[q][4 * i + 1], zz[q][4 * i + 2], zz[q][4 * i + 3]); }
;     }
; #pragma unroll
;     for (int q = 0; q < 2; ++q) {
;       float ss = 0.f;
; #pragma unroll
;       for (int i = 0; i < 16; ++i) ss += v[q][i] * v[q][i];
;       ss += __int_as_float(__builtin_amdgcn_update_dpp(0, __float_as_int(ss), 0xB1, 0xF, 0xF, true));
;       ss += __int_as_float(__builtin_amdgcn_update_dpp(0, __float_as_int(ss), 0x4E, 0xF, 0xF, true));
;       ss += __int_as_float(__builtin_amdgcn_update_dpp(0, __float_as_int(ss), 0x141, 0xF, 0xF, true));
;       const float rs = rsqrtf(ss * (1.0f / 128.f) + EPS);
;       if (q == 0 || two) {
;         const size_t o = (size_t)rr[q] * D + lane * 16;
;         float w[16];
; #pragma unroll
;         for (int i = 0; i < 16; ++i) w[i] = v[q][i] * rs * gpv[i] * siluf_(zz[q][i]);
.LBB0_2032:
	s_waitcnt vmcnt(2)
	v_lshl_add_u64 v[16:17], v[30:31], 0, s[16:17]
	global_load_dwordx4 v[34:37], v[16:17], off offset:16
	v_add_co_u32_e32 v16, vcc, s9, v30
	s_nop 1
	v_addc_co_u32_e32 v17, vcc, -1, v31, vcc
	global_load_dwordx4 v[38:41], v[16:17], off offset:-28
	v_add_co_u32_e32 v16, vcc, 0xeff00000, v30
	s_nop 0
	v_addc_co_u32_e32 v17, vcc, -1, v31, vcc
	global_load_dwordx4 v[42:45], v[16:17], off offset:-28
	v_lshl_add_u64 v[16:17], v[30:31], 0, s[14:15]
	global_load_dwordx4 v[46:49], v[16:17], off offset:16
	v_add_u32_e32 v16, s25, v24
	v_cmp_gt_i32_e32 vcc, s18, v16
	v_cndmask_b32_e32 v16, v24, v16, vcc
	v_ashrrev_i32_e32 v17, 31, v16
	v_lshlrev_b64 v[32:33], 11, v[16:17]
	v_lshl_or_b32 v16, v26, 1, v32
	v_mov_b32_e32 v17, v33
	v_lshl_add_u64 v[18:19], s[4:5], 0, v[16:17]
	global_load_dwordx4 v[52:55], v[18:19], off
	global_load_dwordx4 v[56:59], v[18:19], off offset:16
	v_lshl_add_u64 v[50:51], s[2:3], 0, v[16:17]
	global_load_dwordx4 v[20:23], v[50:51], off offset:16
	global_load_dwordx4 v[16:19], v[50:51], off
	s_waitcnt vmcnt(7)
	v_and_b32_e32 v65, 0xffff0000, v34
	v_lshlrev_b32_e32 v64, 16, v34
	v_and_b32_e32 v63, 0xffff0000, v35
	v_lshlrev_b32_e32 v62, 16, v35
	v_and_b32_e32 v61, 0xffff0000, v36
	v_lshlrev_b32_e32 v60, 16, v36
	v_mul_f32_e32 v100, 0xbfb8aa3b, v65
	v_exp_f32_e32 v103, v100
	v_and_b32_e32 v51, 0xffff0000, v37
	v_lshlrev_b32_e32 v50, 16, v37
	s_waitcnt vmcnt(6)
	v_and_b32_e32 v73, 0xffff0000, v38
	v_lshlrev_b32_e32 v72, 16, v38
	v_mul_f32_e32 v27, 0xbfb8aa3b, v72
	v_mul_f32_e32 v34, 0xbfb8aa3b, v73
	v_lshlrev_b32_e32 v70, 16, v39
	v_exp_f32_e32 v27, v27
	v_exp_f32_e32 v94, v34
	v_and_b32_e32 v71, 0xffff0000, v39
	v_mul_f32_e32 v35, 0xbfb8aa3b, v70
	v_mul_f32_e32 v36, 0xbfb8aa3b, v71
	v_exp_f32_e32 v95, v35
	v_exp_f32_e32 v96, v36
	s_waitcnt vmcnt(4)
	v_lshlrev_b32_e32 v82, 16, v46
	v_and_b32_e32 v83, 0xffff0000, v46
	v_lshlrev_b32_e32 v84, 16, v47
	v_and_b32_e32 v85, 0xffff0000, v47
	v_add_f32_e32 v27, 1.0, v27
	v_lshlrev_b32_e32 v87, 16, v48
	s_waitcnt vmcnt(3)
	v_lshlrev_b32_e32 v46, 16, v53
	v_and_b32_e32 v47, 0xffff0000, v53
	v_add_f32_e32 v53, 1.0, v94
	v_and_b32_e32 v86, 0xffff0000, v48
	v_lshlrev_b32_e32 v89, 16, v49
	v_and_b32_e32 v88, 0xffff0000, v49
	v_lshlrev_b32_e32 v48, 16, v52
	v_and_b32_e32 v49, 0xffff0000, v52
	v_rcp_f32_e32 v52, v27
	v_rcp_f32_e32 v53, v53
	v_add_f32_e32 v27, 1.0, v95
	v_lshlrev_b32_e32 v68, 16, v40
	v_lshlrev_b32_e32 v78, 16, v44
	v_and_b32_e32 v79, 0xffff0000, v44
	v_lshlrev_b32_e32 v80, 16, v45
	v_and_b32_e32 v81, 0xffff0000, v45
	v_lshlrev_b32_e32 v44, 16, v54
	v_and_b32_e32 v45, 0xffff0000, v54
	v_rcp_f32_e32 v54, v27
	v_add_f32_e32 v27, 1.0, v96
	v_and_b32_e32 v69, 0xffff0000, v40
	v_lshlrev_b32_e32 v74, 16, v42
	v_and_b32_e32 v75, 0xffff0000, v42
	v_lshlrev_b32_e32 v76, 16, v43
	v_and_b32_e32 v77, 0xffff0000, v43
	v_lshlrev_b32_e32 v42, 16, v55
	v_and_b32_e32 v43, 0xffff0000, v55
	v_rcp_f32_e32 v55, v27
	v_mul_f32_e32 v27, 0xbfb8aa3b, v68
	v_pk_mul_f32 v[52:53], v[52:53], v[72:73]
	v_exp_f32_e32 v27, v27
	v_mul_f32_e32 v72, 0xbfb8aa3b, v69
	v_exp_f32_e32 v95, v72
	v_lshlrev_b32_e32 v66, 16, v41
	v_add_f32_e32 v27, 1.0, v27
	v_and_b32_e32 v67, 0xffff0000, v41
	v_rcp_f32_e32 v94, v27
	v_add_f32_e32 v27, 1.0, v95
	v_mul_f32_e32 v95, 0xbfb8aa3b, v66
	v_exp_f32_e32 v96, v95
	v_mul_f32_e32 v95, 0xbfb8aa3b, v67
	v_exp_f32_e32 v97, v95
	v_rcp_f32_e32 v95, v27
	v_add_f32_e32 v27, 1.0, v96
	v_rcp_f32_e32 v96, v27
	v_add_f32_e32 v27, 1.0, v97
	v_rcp_f32_e32 v97, v27
	v_mul_f32_e32 v27, 0xbfb8aa3b, v64
	v_exp_f32_e32 v27, v27
	s_waitcnt vmcnt(2)
	v_lshlrev_b32_e32 v36, 16, v58
	v_and_b32_e32 v37, 0xffff0000, v58
	v_lshlrev_b32_e32 v34, 16, v59
	v_add_f32_e32 v27, 1.0, v27
	v_and_b32_e32 v35, 0xffff0000, v59
	v_pk_mul_f32 v[58:59], v[74:75], v[74:75]
	v_rcp_f32_e32 v102, v27
	v_add_f32_e32 v27, 1.0, v103
	v_lshlrev_b32_e32 v40, 16, v56
	v_and_b32_e32 v41, 0xffff0000, v56
	v_lshlrev_b32_e32 v38, 16, v57
	v_and_b32_e32 v39, 0xffff0000, v57
	v_pk_mul_f32 v[56:57], v[76:77], v[76:77]
	v_rcp_f32_e32 v103, v27
	v_add_f32_e32 v27, v58, v59
	v_add_f32_e32 v27, v27, v56
	v_pk_mul_f32 v[72:73], v[78:79], v[78:79]
	v_add_f32_e32 v27, v57, v27
	v_add_f32_e32 v27, v72, v27
	v_pk_mul_f32 v[54:55], v[54:55], v[70:71]
	v_pk_mul_f32 v[70:71], v[80:81], v[80:81]
	v_add_f32_e32 v27, v73, v27
	v_add_f32_e32 v27, v70, v27
	v_pk_mul_f32 v[100:101], v[82:83], v[82:83]
	v_add_f32_e32 v27, v71, v27
	v_add_f32_e32 v27, v100, v27
	v_pk_mul_f32 v[98:99], v[84:85], v[84:85]
	v_add_f32_e32 v27, v101, v27
	v_add_f32_e32 v27, v98, v27
	v_pk_mul_f32 v[90:91], v[86:87], v[86:87]
	v_add_f32_e32 v27, v99, v27
	v_add_f32_e32 v27, v91, v27
	v_pk_mul_f32 v[92:93], v[88:89], v[88:89]
	v_add_f32_e32 v27, v90, v27
	v_add_f32_e32 v27, v93, v27
	v_add_f32_e32 v27, v92, v27
	v_pk_mul_f32 v[58:59], v[96:97], v[66:67]
	v_pk_mul_f32 v[64:65], v[102:103], v[64:65]
	v_add_f32_dpp v27, v27, v27 quad_perm:[1,0,3,2] row_mask:0xf bank_mask:0xf bound_ctrl:1
	s_nop 1
	v_add_f32_dpp v27, v27, v27 quad_perm:[2,3,0,1] row_mask:0xf bank_mask:0xf bound_ctrl:1
	s_nop 1
	v_add_f32_dpp v27, v27, v27 row_half_mirror row_mask:0xf bank_mask:0xf bound_ctrl:1
	v_fmamk_f32 v27, v27, 0x3c000000, v25
	v_mul_f32_e32 v56, 0x4b800000, v27
	v_cmp_gt_f32_e64 s[6:7], s19, v27
	s_nop 1
	v_cndmask_b32_e64 v27, v27, v56, s[6:7]
	v_rsq_f32_e32 v27, v27
	v_pk_mul_f32 v[56:57], v[94:95], v[68:69]
	v_mul_f32_e32 v66, 0x45800000, v27
	v_cndmask_b32_e64 v66, v27, v66, s[6:7]
	v_pk_mul_f32 v[68:69], v[66:67], v[74:75] op_sel_hi:[0,1]
	v_pk_mul_f32 v[68:69], v[12:13], v[68:69]
	v_mul_f32_e32 v27, 0xbfb8aa3b, v62
	v_pk_mul_f32 v[52:53], v[68:69], v[52:53]
; DI float siluf_(float x) { return x * sigmoidf_(x); }
; DI void st_bf4(bf16_t* p, float a, float b, float c, float d) { uint2 v; v.x = pack2(a, b); v.y = pack2(c, d); *(uint2*)p = v; }
; DI void phase_onorm(const Params& p, const Sub& s) {
;     ...
;     for (int q = 0; q < 2; ++q) {
;       float ss = 0.f;
; #pragma unroll
;       for (int i = 0; i < 16; ++i) ss += v[q][i] * v[q][i];
;       ss += __int_as_float(__builtin_amdgcn_update_dpp(0, __float_as_int(ss), 0xB1, 0xF, 0xF, true));
;       ss += __int_as_float(__builtin_amdgcn_update_dpp(0, __float_as_int(ss), 0x4E, 0xF, 0xF, true));
;       ss += __int_as_float(__builtin_amdgcn_update_dpp(0, __float_as_int(ss), 0x141, 0xF, 0xF, true));
;       const float rs = rsqrtf(ss * (1.0f / 128.f) + EPS);
;       if (q == 0 || two) {
;         const size_t o = (size_t)rr[q] * D + lane * 16;
;         float w[16];
; #pragma unroll
;         for (int i = 0; i < 16; ++i) w[i] = v[q][i] * rs * gpv[i] * siluf_(zz[q][i]);
; #pragma unroll
;         for (int i = 0; i < 4; ++i) st_bf4(on + o + i * 4, w[4 * i], w[4 * i + 1], w[4 * i + 2], w[4 * i + 3]);
	v_pk_mul_f32 v[68:69], v[66:67], v[76:77] op_sel_hi:[0,1]
	v_pk_mul_f32 v[68:69], v[14:15], v[68:69]
	v_exp_f32_e32 v27, v27
	v_pk_mul_f32 v[54:55], v[68:69], v[54:55]
	v_pk_mul_f32 v[68:69], v[66:67], v[78:79] op_sel_hi:[0,1]
	v_pk_mul_f32 v[68:69], v[8:9], v[68:69]
	v_add_f32_e32 v27, 1.0, v27
	v_pk_mul_f32 v[56:57], v[68:69], v[56:57]
	v_pk_mul_f32 v[68:69], v[66:67], v[80:81] op_sel_hi:[0,1]
	v_pk_mul_f32 v[68:69], v[10:11], v[68:69]
	s_nop 0
	v_pk_mul_f32 v[58:59], v[68:69], v[58:59]
	v_pk_mul_f32 v[68:69], v[66:67], v[82:83] op_sel_hi:[0,1]
	v_mul_f32_e32 v67, 0xbfb8aa3b, v63
	v_exp_f32_e32 v67, v67
	v_pk_mul_f32 v[68:69], v[4:5], v[68:69]
	v_pk_mul_f32 v[70:71], v[66:67], v[84:85] op_sel_hi:[0,1]
	v_pk_mul_f32 v[64:65], v[68:69], v[64:65]
	v_rcp_f32_e32 v68, v27
	v_add_f32_e32 v27, 1.0, v67
	v_rcp_f32_e32 v69, v27
	v_mul_f32_e32 v27, 0xbfb8aa3b, v60
	v_exp_f32_e32 v27, v27
	v_mul_f32_e32 v67, 0xbfb8aa3b, v61
	v_exp_f32_e32 v67, v67
	v_pk_mul_f32 v[62:63], v[68:69], v[62:63]
	v_add_f32_e32 v27, 1.0, v27
	v_rcp_f32_e32 v68, v27
	v_add_f32_e32 v27, 1.0, v67
	v_pk_mul_f32 v[70:71], v[6:7], v[70:71]
	v_rcp_f32_e32 v69, v27
	v_mul_f32_e32 v27, 0xbfb8aa3b, v50
	v_pk_mul_f32 v[62:63], v[62:63], v[70:71]
	v_pk_mul_f32 v[70:71], v[66:67], v[86:87] op_sel_hi:[0,1]
	v_exp_f32_e32 v27, v27
	v_mul_f32_e32 v67, 0xbfb8aa3b, v51
	v_exp_f32_e32 v67, v67
	v_pk_mul_f32 v[60:61], v[68:69], v[60:61]
	v_add_f32_e32 v27, 1.0, v27
	v_rcp_f32_e32 v68, v27
	v_add_f32_e32 v27, 1.0, v67
	v_rcp_f32_e32 v69, v27
	v_pk_mul_f32 v[66:67], v[66:67], v[88:89] op_sel_hi:[0,1]
	v_pk_mul_f32 v[70:71], v[0:1], v[70:71] op_sel:[0,1] op_sel_hi:[1,0]
	v_pk_mul_f32 v[66:67], v[2:3], v[66:67] op_sel:[0,1] op_sel_hi:[1,0]
	v_pk_mul_f32 v[50:51], v[68:69], v[50:51]
	v_pk_mul_f32 v[60:61], v[60:61], v[70:71]
	v_pk_mul_f32 v[66:67], v[50:51], v[66:67]
	v_cvt_pk_bf16_f32 v50, v52, v53
	v_cvt_pk_bf16_f32 v51, v54, v55
	v_cvt_pk_bf16_f32 v52, v56, v57
	v_cvt_pk_bf16_f32 v53, v58, v59
	global_store_dwordx4 v[30:31], v[50:53], off offset:-28
	v_pk_mul_f32 v[54:55], v[44:45], v[44:45]
	v_pk_mul_f32 v[56:57], v[42:43], v[42:43]
	v_cvt_pk_bf16_f32 v50, v64, v65
	v_cvt_pk_bf16_f32 v51, v62, v63
	v_cvt_pk_bf16_f32 v52, v60, v61
	v_cvt_pk_bf16_f32 v53, v66, v67
	global_store_dwordx4 v[30:31], v[50:53], off offset:-12
	v_pk_mul_f32 v[58:59], v[40:41], v[40:41]
	v_pk_mul_f32 v[60:61], v[38:39], v[38:39]
	v_pk_mul_f32 v[50:51], v[48:49], v[48:49]
	v_pk_mul_f32 v[52:53], v[46:47], v[46:47]
	v_add_f32_e32 v27, v50, v51
	v_add_f32_e32 v27, v27, v52
	v_add_f32_e32 v27, v53, v27
	v_add_f32_e32 v27, v27, v54
	v_add_f32_e32 v27, v55, v27
	v_add_f32_e32 v27, v56, v27
	v_add_f32_e32 v27, v57, v27
	v_add_f32_e32 v27, v27, v58
	v_add_f32_e32 v27, v59, v27
	v_add_f32_e32 v27, v60, v27
	v_pk_mul_f32 v[62:63], v[36:37], v[36:37]
	v_add_f32_e32 v27, v61, v27
	v_add_f32_e32 v27, v27, v62
	v_pk_mul_f32 v[64:65], v[34:35], v[34:35]
	v_add_f32_e32 v27, v63, v27
	v_add_f32_e32 v27, v64, v27
	v_add_f32_e32 v27, v65, v27
	s_nop 1
	v_add_f32_dpp v27, v27, v27 quad_perm:[1,0,3,2] row_mask:0xf bank_mask:0xf bound_ctrl:1
	s_nop 1
	v_add_f32_dpp v27, v27, v27 quad_perm:[2,3,0,1] row_mask:0xf bank_mask:0xf bound_ctrl:1
	s_nop 1
	v_mov_b32_dpp v50, v27 row_half_mirror row_mask:0xf bank_mask:0xf bound_ctrl:1
	s_and_saveexec_b64 s[6:7], vcc
	s_cbranch_execz .LBB0_2031
; DI float siluf_(float x) { return x * sigmoidf_(x); }
; DI void st_bf4(bf16_t* p, float a, float b, float c, float d) { uint2 v; v.x = pack2(a, b); v.y = pack2(c, d); *(uint2*)p = v; }
; DI void phase_onorm(const Params& p, const Sub& s) {
;     ...
;       const float rs = rsqrtf(ss * (1.0f / 128.f) + EPS);
;       if (q == 0 || two) {
;         const size_t o = (size_t)rr[q] * D + lane * 16;
;         float w[16];
; #pragma unroll
;         for (int i = 0; i < 16; ++i) w[i] = v[q][i] * rs * gpv[i] * siluf_(zz[q][i]);
; #pragma unroll
;         for (int i = 0; i < 4; ++i) st_bf4(on + o + i * 4, w[4 * i], w[4 * i + 1], w[4 * i + 2], w[4 * i + 3]);
	s_waitcnt vmcnt(2)
	v_and_b32_e32 v59, 0xffff0000, v17
	v_lshlrev_b32_e32 v58, 16, v17
	v_add_f32_e32 v17, v27, v50
	v_fmamk_f32 v17, v17, 0x3c000000, v25
	v_mul_f32_e32 v27, 0x4b800000, v17
	v_cmp_gt_f32_e32 vcc, s19, v17
	v_lshlrev_b32_e32 v60, 16, v16
	v_and_b32_e32 v61, 0xffff0000, v16
	v_cndmask_b32_e32 v17, v17, v27, vcc
	v_rsq_f32_e32 v17, v17
	v_mul_f32_e32 v27, 0xbfb8aa3b, v60
	v_exp_f32_e32 v27, v27
	v_and_b32_e32 v57, 0xffff0000, v19
	v_mul_f32_e32 v16, 0x45800000, v17
	v_cndmask_b32_e32 v16, v17, v16, vcc
	v_add_f32_e32 v17, 1.0, v27
	v_mul_f32_e32 v27, 0xbfb8aa3b, v61
	v_exp_f32_e32 v27, v27
	v_rcp_f32_e32 v50, v17
	v_pk_mul_f32 v[48:49], v[16:17], v[48:49] op_sel_hi:[0,1]
	v_lshlrev_b32_e32 v56, 16, v19
	v_add_f32_e32 v17, 1.0, v27
	v_rcp_f32_e32 v51, v17
	v_mul_f32_e32 v17, 0xbfb8aa3b, v58
	v_exp_f32_e32 v17, v17
	v_mul_f32_e32 v27, 0xbfb8aa3b, v59
	v_exp_f32_e32 v27, v27
	v_and_b32_e32 v19, 0xffff0000, v18
	v_add_f32_e32 v17, 1.0, v17
	v_lshlrev_b32_e32 v18, 16, v18
	v_pk_mul_f32 v[50:51], v[50:51], v[60:61]
	v_rcp_f32_e32 v60, v17
	v_add_f32_e32 v17, 1.0, v27
	v_rcp_f32_e32 v61, v17
	v_pk_mul_f32 v[46:47], v[16:17], v[46:47] op_sel_hi:[0,1]
	v_mul_f32_e32 v17, 0xbfb8aa3b, v18
	v_exp_f32_e32 v17, v17
	v_mul_f32_e32 v27, 0xbfb8aa3b, v19
	v_exp_f32_e32 v27, v27
	v_pk_mul_f32 v[48:49], v[12:13], v[48:49]
	v_pk_mul_f32 v[46:47], v[14:15], v[46:47]
	v_pk_mul_f32 v[48:49], v[50:51], v[48:49]
	v_pk_mul_f32 v[50:51], v[60:61], v[58:59]
	v_add_f32_e32 v17, 1.0, v17
	v_pk_mul_f32 v[46:47], v[50:51], v[46:47]
	v_rcp_f32_e32 v50, v17
	v_pk_mul_f32 v[44:45], v[16:17], v[44:45] op_sel_hi:[0,1]
	v_add_f32_e32 v17, 1.0, v27
	v_rcp_f32_e32 v51, v17
	v_mul_f32_e32 v17, 0xbfb8aa3b, v56
	v_exp_f32_e32 v17, v17
	v_mul_f32_e32 v27, 0xbfb8aa3b, v57
	v_exp_f32_e32 v27, v27
	v_pk_mul_f32 v[44:45], v[8:9], v[44:45]
	v_pk_mul_f32 v[18:19], v[50:51], v[18:19]
	v_add_f32_e32 v17, 1.0, v17
	v_and_b32_e32 v55, 0xffff0000, v21
	v_lshlrev_b32_e32 v54, 16, v21
	v_and_b32_e32 v21, 0xffff0000, v20
	v_lshlrev_b32_e32 v20, 16, v20
	v_pk_mul_f32 v[18:19], v[18:19], v[44:45]
	v_rcp_f32_e32 v44, v17
	v_pk_mul_f32 v[42:43], v[16:17], v[42:43] op_sel_hi:[0,1]
	v_add_f32_e32 v17, 1.0, v27
	v_rcp_f32_e32 v45, v17
	v_mul_f32_e32 v17, 0xbfb8aa3b, v20
	v_exp_f32_e32 v17, v17
	v_mul_f32_e32 v27, 0xbfb8aa3b, v21
	v_exp_f32_e32 v27, v27
	v_and_b32_e32 v53, 0xffff0000, v23
	v_add_f32_e32 v17, 1.0, v17
	v_rcp_f32_e32 v50, v17
	v_add_f32_e32 v17, 1.0, v27
	v_rcp_f32_e32 v51, v17
	v_pk_mul_f32 v[40:41], v[16:17], v[40:41] op_sel_hi:[0,1]
	v_mul_f32_e32 v17, 0xbfb8aa3b, v54
	v_exp_f32_e32 v17, v17
	v_mul_f32_e32 v27, 0xbfb8aa3b, v55
	v_exp_f32_e32 v27, v27
	v_pk_mul_f32 v[40:41], v[4:5], v[40:41]
	v_pk_mul_f32 v[20:21], v[50:51], v[20:21]
	v_add_f32_e32 v17, 1.0, v17
	v_lshlrev_b32_e32 v52, 16, v23
	v_and_b32_e32 v23, 0xffff0000, v22
	v_lshlrev_b32_e32 v22, 16, v22
	v_pk_mul_f32 v[20:21], v[20:21], v[40:41]
	v_rcp_f32_e32 v40, v17
	v_pk_mul_f32 v[38:39], v[16:17], v[38:39] op_sel_hi:[0,1]
	v_add_f32_e32 v17, 1.0, v27
	v_rcp_f32_e32 v41, v17
	v_mul_f32_e32 v17, 0xbfb8aa3b, v22
	v_exp_f32_e32 v17, v17
	v_mul_f32_e32 v27, 0xbfb8aa3b, v23
	v_exp_f32_e32 v27, v27
	v_pk_mul_f32 v[38:39], v[6:7], v[38:39]
	v_pk_mul_f32 v[40:41], v[40:41], v[54:55]
	v_add_f32_e32 v17, 1.0, v17
	v_pk_mul_f32 v[38:39], v[40:41], v[38:39]
	v_rcp_f32_e32 v40, v17
	v_pk_mul_f32 v[36:37], v[16:17], v[36:37] op_sel_hi:[0,1]
	v_add_f32_e32 v17, 1.0, v27
	v_rcp_f32_e32 v41, v17
	v_mul_f32_e32 v17, 0xbfb8aa3b, v52
	v_exp_f32_e32 v17, v17
	v_mul_f32_e32 v27, 0xbfb8aa3b, v53
	v_exp_f32_e32 v27, v27
	v_pk_mul_f32 v[22:23], v[40:41], v[22:23]
	v_add_f32_e32 v17, 1.0, v17
	v_rcp_f32_e32 v40, v17
	v_add_f32_e32 v17, 1.0, v27
	v_rcp_f32_e32 v41, v17
	v_pk_mul_f32 v[42:43], v[10:11], v[42:43]
	v_pk_mul_f32 v[44:45], v[44:45], v[56:57]
	v_pk_mul_f32 v[16:17], v[16:17], v[34:35] op_sel_hi:[0,1]
	v_pk_mul_f32 v[42:43], v[44:45], v[42:43]
	v_pk_mul_f32 v[36:37], v[0:1], v[36:37]
	v_pk_mul_f32 v[16:17], v[2:3], v[16:17]
	v_pk_mul_f32 v[34:35], v[40:41], v[52:53]
	v_pk_mul_f32 v[22:23], v[22:23], v[36:37]
	v_pk_mul_f32 v[34:35], v[34:35], v[16:17]
	v_lshl_add_u64 v[32:33], v[28:29], 0, v[32:33]
	v_cvt_pk_bf16_f32 v16, v48, v49
	v_cvt_pk_bf16_f32 v17, v46, v47
	v_cvt_pk_bf16_f32 v18, v18, v19
	v_cvt_pk_bf16_f32 v19, v42, v43
	global_store_dwordx4 v[32:33], v[16:19], off
	s_nop 1
	v_cvt_pk_bf16_f32 v16, v20, v21
	v_cvt_pk_bf16_f32 v17, v38, v39
	v_cvt_pk_bf16_f32 v18, v22, v23
	v_cvt_pk_bf16_f32 v19, v34, v35
	global_store_dwordx4 v[32:33], v[16:19], off offset:16
	s_branch .LBB0_2031
